# diff fast loop: static s_setprio 1 for waves 4-7 for the whole tile loop, per-segment priority flips removed
# baseline (speedup 1.0000x reference)
.LBB0_457:
	v_readlane_b32 s2, v254, 36
	s_add_i32 s7, s6, s2
	s_cmpk_gt_i32 s7, 0x7ff
	s_mov_b64 s[4:5], -1
	s_cbranch_scc1 .LBB0_456
	v_readlane_b32 s2, v253, 51
	v_readlane_b32 s4, v253, 49
	s_add_i32 s8, s6, s2
	s_ashr_i32 s9, s7, 5
	v_readlane_b32 s5, v253, 50
	s_and_b64 s[4:5], s[4:5], exec
	s_cselect_b32 s4, s85, s7
	s_cselect_b32 s5, s8, s9
	s_lshl_b32 s4, s4, 7
	s_and_b32 s16, s4, 0xf80
	s_lshl_b32 s4, s5, 7
	s_ashr_i32 s7, s5, 3
	s_and_b32 s8, s4, 0x380
	s_lshl_b32 s9, s7, 12
	s_lshl_b32 s10, s7, 8
	s_lshr_b32 s7, s8, 6
	s_add_i32 s10, s10, 0x8000
	s_mul_i32 s11, s7, 0x8800
	s_ashr_i32 s17, s9, 31
	v_mbcnt_lo_u32_b32 v0, -1, 0
	v_mbcnt_hi_u32_b32 v0, -1, v0
	s_add_u32 s4, s11, s9
	v_add_u32_e32 v187, s69, v0
	s_addc_u32 s5, 0, s17
	v_and_b32_e32 v0, 7, v187
	v_bfe_u32 v188, v187, 4, 2
	v_bitop3_b32 v0, v188, v0, s83 bitop3:0x36
	s_lshl_b64 s[4:5], s[4:5], 7
	v_and_or_b32 v0, v187, 56, v0
	s_add_u32 s12, s95, s4
	v_lshl_or_b32 v212, v0, 4, s46
	s_addc_u32 s13, s3, s5
	s_mov_b32 s19, m0
	s_mov_b32 m0, s23
	s_nop 0
	global_load_lds_dwordx4 v212, s[12:13]
	s_mov_b32 m0, s19
	s_add_i32 s12, s11, 0x8800
	s_add_u32 s28, s12, s9
	s_addc_u32 s29, 0, s17
	s_lshl_b64 s[28:29], s[28:29], 7
	v_bfe_u32 v5, v187, 5, 1
	v_lshlrev_b32_e32 v190, 4, v187
	s_add_u32 s28, s95, s28
	v_or_b32_e32 v2, s25, v5
	v_and_b32_e32 v3, 0x1c0, v190
	v_lshlrev_b32_e32 v189, 3, v187
	s_addc_u32 s29, s3, s29
	s_add_i32 s13, s23, 0x2000
	v_lshl_or_b32 v2, v2, 9, v3
	v_and_b32_e32 v6, 24, v189
	v_readlane_b32 s2, v253, 62
	s_add_u32 s4, s14, s4
	s_mov_b32 s17, m0
	s_mov_b32 m0, s13
	s_nop 0
	global_load_lds_dwordx4 v212, s[28:29]
	s_mov_b32 m0, s17
	s_addc_u32 s5, s15, s5
	v_or3_b32 v2, v2, s2, v6
	v_readlane_b32 s2, v253, 63
	s_add_i32 s13, s23, 0x4000
	v_and_b32_e32 v191, 31, v187
	v_add_lshl_u32 v222, v2, s2, 1
	s_mov_b32 s17, m0
	s_mov_b32 m0, s13
	s_nop 0
	global_load_lds_dwordx4 v222, s[4:5]
	s_mov_b32 m0, s17
	v_readlane_b32 s2, v254, 26
	s_add_i32 s13, s23, 0x6000
	v_lshlrev_b32_e32 v0, 4, v5
	v_add_lshl_u32 v223, v2, s2, 1
	s_mov_b32 s17, m0
	s_mov_b32 m0, s13
	s_nop 0
	global_load_lds_dwordx4 v223, s[4:5]
	s_mov_b32 m0, s17
	s_or_b32 s13, s9, 64
	s_ashr_i32 s17, s13, 31
	s_add_u32 s4, s11, s13
	s_addc_u32 s5, 0, s17
	s_lshl_b64 s[4:5], s[4:5], 7
	s_add_u32 s28, s95, s4
	s_addc_u32 s29, s3, s5
	s_add_i32 s19, s23, 0x8000
	s_mov_b32 s20, m0
	s_mov_b32 m0, s19
	s_nop 0
	global_load_lds_dwordx4 v212, s[28:29]
	s_mov_b32 m0, s20
	s_add_u32 s28, s12, s13
	s_addc_u32 s29, 0, s17
	s_lshl_b64 s[28:29], s[28:29], 7
	s_add_u32 s28, s95, s28
	s_addc_u32 s29, s3, s29
	s_add_i32 s13, s23, 0xa000
	s_mov_b32 s17, m0
	s_mov_b32 m0, s13
	s_nop 0
	global_load_lds_dwordx4 v212, s[28:29]
	s_mov_b32 m0, s17
	s_add_u32 s4, s14, s4
	s_addc_u32 s5, s15, s5
	s_add_i32 s13, s23, 0xc000
	s_mov_b32 s17, m0
	s_mov_b32 m0, s13
	s_nop 0
	global_load_lds_dwordx4 v222, s[4:5]
	s_mov_b32 m0, s17
	v_readlane_b32 s2, v254, 33
	s_add_i32 s13, s23, 0xe000
	s_mov_b32 s17, m0
	s_mov_b32 m0, s13
	s_nop 0
	global_load_lds_dwordx4 v223, s[4:5]
	s_mov_b32 m0, s17
	s_add_i32 s4, s7, s2
	v_readlane_b32 s2, v253, 53
	s_or_b32 s5, s16, s2
	s_or_b32 s7, s5, s9
	v_or_b32_e32 v2, s7, v191
	v_ashrrev_i32_e32 v3, 31, v2
	v_mad_u64_u32 v[2:3], s[4:5], s4, v217, v[2:3]
	v_lshlrev_b64 v[2:3], 7, v[2:3]
	v_lshl_add_u64 v[2:3], s[58:59], 0, v[2:3]
	v_lshl_add_u64 v[2:3], v[2:3], 0, v[0:1]
	global_load_dwordx4 v[144:147], v[2:3], off offset:96
	global_load_dwordx4 v[148:151], v[2:3], off offset:64
	global_load_dwordx4 v[152:155], v[2:3], off offset:32
	global_load_dwordx4 v[156:159], v[2:3], off
	v_lshrrev_b32_e32 v0, 1, v187
	v_lshrrev_b32_e32 v7, 2, v187
	v_lshlrev_b32_e32 v193, 2, v5
	v_lshlrev_b32_e32 v8, 1, v187
	v_bfe_u32 v9, v187, 1, 3
	v_bitop3_b32 v0, v5, v0, 7 bitop3:0x78
	v_and_or_b32 v7, v7, 3, v193
	v_lshlrev_b32_e32 v192, 3, v5
	v_and_b32_e32 v8, 32, v8
	v_bitop3_b32 v10, v5, v9, 2 bitop3:0x36
	v_bitop3_b32 v11, v5, v9, 4 bitop3:0x36
	v_bitop3_b32 v5, v5, v9, 6 bitop3:0x36
	v_lshlrev_b32_e32 v228, 4, v0
	v_lshlrev_b32_e32 v0, 6, v7
	v_mov_b32_e32 v14, v1
	v_mov_b32_e32 v15, v1
	v_mov_b32_e32 v2, v1
	v_mov_b32_e32 v3, v1
	v_mov_b32_e32 v4, v1
	v_lshlrev_b32_e32 v226, 4, v10
	v_lshlrev_b32_e32 v225, 4, v11
	v_lshlrev_b32_e32 v224, 4, v5
	v_or3_b32 v210, v0, v8, v6
	v_mov_b32_e32 v0, v1
	v_mov_b32_e32 v5, v1
	v_mov_b32_e32 v6, v1
	v_mov_b32_e32 v7, v1
	v_mov_b32_e32 v8, v1
	v_mov_b32_e32 v9, v1
	v_mov_b32_e32 v10, v1
	v_mov_b32_e32 v11, v1
	v_mov_b32_e32 v12, v1
	v_mov_b32_e32 v13, v1
	v_mov_b64_e32 v[78:79], v[14:15]
	v_mov_b64_e32 v[62:63], v[14:15]
	v_mov_b64_e32 v[46:47], v[14:15]
	v_mov_b64_e32 v[30:31], v[14:15]
	v_mov_b64_e32 v[94:95], v[14:15]
	s_mov_b32 s13, 2
	s_mov_b32 s19, 0
	v_and_b32_e32 v194, 63, v187
	v_lshl_add_u32 v227, v191, 7, s21
	v_add_u32_e32 v195, 0, v210
	s_mov_b64 s[4:5], -1
	v_mov_b32_e32 v209, 0
	v_mov_b32_e32 v140, 0
	v_mov_b32_e32 v141, 0
	v_mov_b32_e32 v142, 0
	v_mov_b32_e32 v143, 0
	v_mov_b32_e32 v136, 0
	v_mov_b32_e32 v137, 0
	v_mov_b32_e32 v138, 0
	v_mov_b32_e32 v139, 0
	v_mov_b32_e32 v132, 0
	v_mov_b32_e32 v133, 0
	v_mov_b32_e32 v134, 0
	v_mov_b32_e32 v135, 0
	v_mov_b32_e32 v128, 0
	v_mov_b32_e32 v129, 0
	v_mov_b32_e32 v130, 0
	v_mov_b32_e32 v131, 0
	v_mov_b64_e32 v[76:77], v[12:13]
	v_mov_b64_e32 v[74:75], v[10:11]
	v_mov_b64_e32 v[72:73], v[8:9]
	v_mov_b64_e32 v[70:71], v[6:7]
	v_mov_b64_e32 v[68:69], v[4:5]
	v_mov_b64_e32 v[66:67], v[2:3]
	v_mov_b64_e32 v[64:65], v[0:1]
	v_mov_b64_e32 v[60:61], v[12:13]
	v_mov_b64_e32 v[58:59], v[10:11]
	v_mov_b64_e32 v[56:57], v[8:9]
	v_mov_b64_e32 v[54:55], v[6:7]
	v_mov_b64_e32 v[52:53], v[4:5]
	v_mov_b64_e32 v[50:51], v[2:3]
	v_mov_b64_e32 v[48:49], v[0:1]
	v_mov_b64_e32 v[44:45], v[12:13]
	v_mov_b64_e32 v[42:43], v[10:11]
	v_mov_b64_e32 v[40:41], v[8:9]
	v_mov_b64_e32 v[38:39], v[6:7]
	v_mov_b64_e32 v[36:37], v[4:5]
	v_mov_b64_e32 v[34:35], v[2:3]
	v_mov_b64_e32 v[32:33], v[0:1]
	v_mov_b64_e32 v[28:29], v[12:13]
	v_mov_b64_e32 v[26:27], v[10:11]
	v_mov_b64_e32 v[24:25], v[8:9]
	v_mov_b64_e32 v[22:23], v[6:7]
	v_mov_b64_e32 v[20:21], v[4:5]
	v_mov_b64_e32 v[18:19], v[2:3]
	v_mov_b64_e32 v[16:17], v[0:1]
	v_mov_b64_e32 v[92:93], v[12:13]
	v_mov_b64_e32 v[90:91], v[10:11]
	v_mov_b64_e32 v[88:89], v[8:9]
	v_mov_b64_e32 v[86:87], v[6:7]
	v_mov_b64_e32 v[84:85], v[4:5]
	v_mov_b64_e32 v[82:83], v[2:3]
	v_mov_b64_e32 v[80:81], v[0:1]
	s_mov_b32 s28, 0
	s_waitcnt vmcnt(0)
	v_mov_b32_e32 v218, s60
	v_mov_b32_e32 v219, s60
	v_mov_b32_e32 v220, s60
	v_mov_b32_e32 v221, s60
	s_add_i32 s20, s19, 0x10000
	s_and_b32 s20, s20, 0x18000
	s_add_i32 s20, s20, s23
	s_add_i32 s62, s13, -2
	s_cmpk_gt_u32 s62, 0x41
	s_cselect_b32 s61, 1, 0
	s_cmp_lt_u32 s62, 62
	s_cselect_b32 s16, 0, 0xffffffc0
	s_cselect_b32 s17, s9, s10
	s_add_i32 s16, s16, s13
	s_lshl_b32 s16, s16, 6
	s_add_i32 s62, s16, s17
	s_ashr_i32 s63, s62, 31
	s_add_u32 s30, s62, s11
	s_addc_u32 s31, s63, 0
	s_lshl_b64 s[30:31], s[30:31], 7
	s_add_u32 s34, s95, s30
	s_addc_u32 s35, s3, s31
	s_add_u32 s16, s62, s12
	s_addc_u32 s17, s63, 0
	s_lshl_b64 s[16:17], s[16:17], 7
	s_add_u32 s16, s95, s16
	s_addc_u32 s17, s3, s17
	s_add_u32 s30, s14, s30
	s_addc_u32 s31, s15, s31
	s_cmp_lg_u32 s21, 0
	s_cbranch_scc0 .Lf_noprio
	s_setprio 1
.Lf_noprio:
	s_branch .Lf_460
.LBB0_459:
	v_mov_b32_e32 v180, v128
	v_mov_b32_e32 v181, v129
	v_mov_b32_e32 v182, v130
	v_mov_b32_e32 v183, v131
	v_mfma_f32_32x32x16_bf16 v[64:79], v[176:179], v[140:143], v[64:79]
	ds_read_b64_tr_b16 v[128:129], v0 offset:24576
	ds_read_b64_tr_b16 v[130:131], v0 offset:25088
	v_sub_f32_e32 v14, v112, v209
	v_exp_f32_e32 v14, v14
	s_mov_b32 s61, s60
	s_mov_b32 s62, s60
	s_mov_b32 s63, s60
	v_mfma_f32_32x32x16_bf16 v[64:79], v[172:175], v[136:139], v[64:79]
	ds_read_b64_tr_b16 v[172:173], v0 offset:25600
	ds_read_b64_tr_b16 v[174:175], v0 offset:26112
	v_sub_f32_e32 v15, v96, v209
	v_exp_f32_e32 v15, v15
	v_mfma_f32_32x32x16_bf16 v[64:79], v[168:171], v[132:135], v[64:79]
	ds_read_b64_tr_b16 v[168:169], v0 offset:26624
	ds_read_b64_tr_b16 v[170:171], v0 offset:27136
	v_sub_f32_e32 v96, v113, v209
	v_exp_f32_e32 v96, v96
	v_mfma_f32_32x32x16_bf16 v[64:79], v[164:167], v[180:183], v[64:79]
	ds_read_b64_tr_b16 v[164:165], v0 offset:27648
	ds_read_b64_tr_b16 v[166:167], v0 offset:28160
	v_sub_f32_e32 v97, v97, v209
	v_exp_f32_e32 v97, v97
	v_mfma_f32_32x32x16_bf16 v[48:63], v[160:163], v[140:143], v[48:63]
	ds_read_b64_tr_b16 v[160:161], v0 offset:28672
	ds_read_b64_tr_b16 v[162:163], v0 offset:29184
	v_sub_f32_e32 v112, v114, v209
	v_exp_f32_e32 v112, v112
	v_mfma_f32_32x32x16_bf16 v[48:63], v[10:13], v[136:139], v[48:63]
	ds_read_b64_tr_b16 v[10:11], v0 offset:29696
	ds_read_b64_tr_b16 v[12:13], v0 offset:30208
	v_sub_f32_e32 v98, v98, v209
	v_exp_f32_e32 v98, v98
	v_mfma_f32_32x32x16_bf16 v[48:63], v[6:9], v[132:135], v[48:63]
	ds_read_b64_tr_b16 v[6:7], v0 offset:30720
	ds_read_b64_tr_b16 v[8:9], v0 offset:31232
	v_sub_f32_e32 v113, v115, v209
	v_exp_f32_e32 v113, v113
	v_mfma_f32_32x32x16_bf16 v[48:63], v[2:5], v[180:183], v[48:63]
	ds_read_b64_tr_b16 v[2:3], v0 offset:31744
	ds_read_b64_tr_b16 v[4:5], v0 offset:32256
	v_sub_f32_e32 v0, v99, v209
	v_exp_f32_e32 v0, v0
	s_waitcnt lgkmcnt(14)
	v_mfma_f32_32x32x16_bf16 v[32:47], v[128:131], v[140:143], v[32:47]
	v_sub_f32_e32 v99, v116, v209
	v_sub_f32_e32 v100, v100, v209
	v_sub_f32_e32 v114, v117, v209
	v_exp_f32_e32 v99, v99
	v_exp_f32_e32 v100, v100
	s_waitcnt lgkmcnt(12)
	v_mfma_f32_32x32x16_bf16 v[32:47], v[172:175], v[136:139], v[32:47]
	v_sub_f32_e32 v101, v101, v209
	v_sub_f32_e32 v115, v118, v209
	v_sub_f32_e32 v102, v102, v209
	v_exp_f32_e32 v114, v114
	v_exp_f32_e32 v101, v101
	s_waitcnt lgkmcnt(10)
	v_mfma_f32_32x32x16_bf16 v[32:47], v[168:171], v[132:135], v[32:47]
	v_sub_f32_e32 v116, v119, v209
	v_sub_f32_e32 v103, v103, v209
	v_sub_f32_e32 v117, v120, v209
	v_exp_f32_e32 v115, v115
	v_exp_f32_e32 v102, v102
	s_waitcnt lgkmcnt(8)
	v_mfma_f32_32x32x16_bf16 v[32:47], v[164:167], v[180:183], v[32:47]
	v_sub_f32_e32 v104, v104, v209
	v_sub_f32_e32 v118, v121, v209
	v_sub_f32_e32 v105, v105, v209
	v_exp_f32_e32 v116, v116
	v_exp_f32_e32 v103, v103
	s_waitcnt lgkmcnt(6)
	v_mfma_f32_32x32x16_bf16 v[16:31], v[160:163], v[140:143], v[16:31]
	v_sub_f32_e32 v119, v122, v209
	v_sub_f32_e32 v106, v106, v209
	v_sub_f32_e32 v120, v123, v209
	v_exp_f32_e32 v117, v117
	v_exp_f32_e32 v104, v104
	s_waitcnt lgkmcnt(4)
	v_mfma_f32_32x32x16_bf16 v[16:31], v[10:13], v[136:139], v[16:31]
	v_sub_f32_e32 v10, v107, v209
	v_sub_f32_e32 v11, v124, v209
	v_sub_f32_e32 v12, v108, v209
	v_exp_f32_e32 v13, v118
	v_exp_f32_e32 v105, v105
	s_waitcnt lgkmcnt(2)
	v_mfma_f32_32x32x16_bf16 v[16:31], v[6:9], v[132:135], v[16:31]
	v_sub_f32_e32 v6, v125, v209
	v_sub_f32_e32 v7, v109, v209
	v_sub_f32_e32 v8, v126, v209
	v_exp_f32_e32 v9, v119
	v_exp_f32_e32 v106, v106
	s_waitcnt lgkmcnt(0)
	v_mfma_f32_32x32x16_bf16 v[16:31], v[2:5], v[180:183], v[16:31]
	v_mov_b64_e32 v[2:3], s[60:61]
	v_mov_b64_e32 v[4:5], s[62:63]
	v_sub_f32_e32 v107, v110, v209
	v_exp_f32_e32 v110, v120
	v_exp_f32_e32 v10, v10
	v_mfma_f32_32x32x16_bf16 v[80:95], v[2:5], v[140:143], v[80:95]
	v_sub_f32_e32 v108, v127, v209
	v_sub_f32_e32 v109, v111, v209
	v_cvt_pk_bf16_f32 v140, v14, v96
	v_exp_f32_e32 v11, v11
	v_exp_f32_e32 v12, v12
	v_cvt_pk_bf16_f32 v143, v115, v116
	v_mfma_f32_32x32x16_bf16 v[80:95], v[2:5], v[136:139], v[80:95]
	v_cvt_pk_bf16_f32 v128, v104, v105
	v_cvt_pk_bf16_f32 v141, v112, v113
	v_cvt_pk_bf16_f32 v136, v117, v13
	v_exp_f32_e32 v6, v6
	v_exp_f32_e32 v7, v7
	v_mfma_f32_32x32x16_bf16 v[80:95], v[2:5], v[132:135], v[80:95]
	v_cvt_pk_bf16_f32 v137, v9, v110
	v_cvt_pk_bf16_f32 v129, v106, v10
	v_cvt_pk_bf16_f32 v132, v15, v97
	v_cvt_pk_bf16_f32 v130, v12, v7
	v_exp_f32_e32 v7, v109
	v_cvt_pk_bf16_f32 v138, v11, v6
	v_exp_f32_e32 v6, v108
	v_cvt_pk_bf16_f32 v133, v98, v0
	v_cvt_pk_bf16_f32 v142, v99, v114
	v_exp_f32_e32 v0, v8
	v_exp_f32_e32 v8, v107
	v_cvt_pk_bf16_f32 v134, v100, v101
	v_cvt_pk_bf16_f32 v135, v102, v103
	v_cvt_pk_bf16_f32 v139, v0, v6
	v_cvt_pk_bf16_f32 v131, v8, v7
	v_mfma_f32_32x32x16_bf16 v[80:95], v[2:5], v[180:183], v[80:95]
	s_add_i32 s28, s28, 1
	s_add_i32 s13, s13, 1
	s_add_i32 s19, s19, 0x8000
	s_cmpk_eq_i32 s13, 0x45
	s_cbranch_scc1 .LBB0_464

.Lf_462:
	s_and_b32 s17, s19, 0x18000
	v_add_u32_e32 v0, s17, v227
	v_add_u32_e32 v2, v0, v228
	ds_read_b128 v[96:99], v2
	ds_read_b128 v[100:103], v2 offset:4096
	v_add_u32_e32 v2, v0, v226
	ds_read_b128 v[180:183], v2
	ds_read_b128 v[230:233], v2 offset:4096
	v_add_u32_e32 v2, v0, v225
	v_add_u32_e32 v0, v0, v224
	s_min_u32 s16, s28, 1
	ds_read_b128 v[234:237], v2
	ds_read_b128 v[238:241], v2 offset:4096
	ds_read_b128 v[242:245], v0
	ds_read_b128 v[246:249], v0 offset:4096
	s_lshl_b32 s16, s16, 15
	s_sub_i32 s16, s19, s16
	s_and_b32 s16, s16, 0x18000
	v_add_u32_e32 v0, s16, v195
	s_waitcnt lgkmcnt(6)
	v_mfma_f32_32x32x16_bf16 v[112:127], v[96:99], v[156:159], 0
	s_add_i32 s22, s13, 1
	s_add_i32 s61, s19, 0x8000
	s_add_i32 s20, s61, 0x10000
	s_and_b32 s20, s20, 0x18000
	v_mfma_f32_32x32x16_bf16 v[96:111], v[100:103], v[156:159], 0
	s_add_i32 s20, s20, s23
	s_add_i32 s62, s22, -2
	s_cmpk_gt_u32 s62, 0x41
	s_cselect_b32 s61, 1, 0
	s_waitcnt lgkmcnt(4)
	v_mfma_f32_32x32x16_bf16 v[112:127], v[180:183], v[152:155], v[112:127]
	s_cmp_lt_u32 s62, 62
	s_cselect_b32 s16, 0, 0xffffffc0
	s_cselect_b32 s17, s9, s10
	s_add_i32 s16, s16, s22
	v_mfma_f32_32x32x16_bf16 v[96:111], v[230:233], v[152:155], v[96:111]
	s_lshl_b32 s16, s16, 6
	s_add_i32 s62, s16, s17
	s_ashr_i32 s63, s62, 31
	s_add_u32 s30, s62, s11
	s_waitcnt lgkmcnt(2)
	v_mfma_f32_32x32x16_bf16 v[112:127], v[234:237], v[148:151], v[112:127]
	s_addc_u32 s31, s63, 0
	s_lshl_b64 s[30:31], s[30:31], 7
	s_add_u32 s34, s95, s30
	s_addc_u32 s35, s3, s31
	v_mfma_f32_32x32x16_bf16 v[96:111], v[238:241], v[148:151], v[96:111]
	s_add_u32 s16, s62, s12
	s_addc_u32 s17, s63, 0
	s_lshl_b64 s[16:17], s[16:17], 7
	s_add_u32 s16, s95, s16
	s_waitcnt lgkmcnt(0)
	v_mfma_f32_32x32x16_bf16 v[112:127], v[242:245], v[144:147], v[112:127]
	s_addc_u32 s17, s3, s17
	s_add_u32 s30, s14, s30
	s_addc_u32 s31, s15, s31
	v_mfma_f32_32x32x16_bf16 v[96:111], v[246:249], v[144:147], v[96:111]
	ds_read_b64_tr_b16 v[176:177], v0 offset:16384
	ds_read_b64_tr_b16 v[178:179], v0 offset:16896
	ds_read_b64_tr_b16 v[172:173], v0 offset:17408
	ds_read_b64_tr_b16 v[174:175], v0 offset:17920
	ds_read_b64_tr_b16 v[168:169], v0 offset:18432
	ds_read_b64_tr_b16 v[170:171], v0 offset:18944
	ds_read_b64_tr_b16 v[164:165], v0 offset:19456
	ds_read_b64_tr_b16 v[166:167], v0 offset:19968
	ds_read_b64_tr_b16 v[160:161], v0 offset:20480
	ds_read_b64_tr_b16 v[162:163], v0 offset:20992
	ds_read_b64_tr_b16 v[10:11], v0 offset:21504
	ds_read_b64_tr_b16 v[12:13], v0 offset:22016
	ds_read_b64_tr_b16 v[6:7], v0 offset:22528
	ds_read_b64_tr_b16 v[8:9], v0 offset:23040
	ds_read_b64_tr_b16 v[2:3], v0 offset:23552
	ds_read_b64_tr_b16 v[4:5], v0 offset:24064
	v_max3_f32 v14, v112, v113, v114
	v_max3_f32 v15, v115, v116, v117
	v_max3_f32 v180, v118, v119, v120
	v_max3_f32 v181, v121, v122, v123
	v_max3_f32 v182, v124, v125, v126
	v_max3_f32 v183, v96, v97, v98
	v_max3_f32 v230, v99, v100, v101
	v_max3_f32 v231, v102, v103, v104
	s_nop 0
	v_max3_f32 v14, v14, v15, v180
	v_max3_f32 v232, v105, v106, v107
	v_max3_f32 v15, v181, v182, v127
	v_max3_f32 v233, v108, v109, v110
	v_max3_f32 v180, v183, v230, v231
	v_max3_f32 v181, v232, v233, v111
	s_nop 0
	v_max3_f32 v14, v14, v15, v180
	v_max_f32_e32 v14, v14, v181
	v_mov_b32_e32 v15, v14
	s_nop 1
	v_permlane32_swap_b32_e32 v15, v14
	v_max_f32_e32 v14, v14, v15
	v_cmp_lt_f32_e32 vcc, 0x42800000, v14
	s_waitcnt lgkmcnt(0)
	s_cbranch_vccz .Lf_459
	s_branch .Lf_to463
